# P0 row loop: non-temporal hint on the 16 once-read x row loads
# speedup vs baseline: 1.0516x; 1.0219x over previous
.LBB0_144:
	global_load_dwordx4 v[188:191], v[206:207], off offset:-2048 nt
	global_load_dwordx4 v[184:187], v[206:207], off offset:-1024 nt
	global_load_dwordx4 v[176:179], v[206:207], off offset:1024 nt
	global_load_dwordx4 v[180:183], v[206:207], off nt
	v_add_u32_e32 v2, s33, v192
	v_add_u32_e32 v210, 5, v2
	v_ashrrev_i32_e32 v211, 31, v210
	s_waitcnt lgkmcnt(0)
	v_lshlrev_b64 v[0:1], 12, v[210:211]
	v_lshl_add_u64 v[0:1], v[198:199], 0, v[0:1]
	global_load_dwordx4 v[132:135], v[0:1], off nt
	global_load_dwordx4 v[124:127], v[0:1], off offset:1024 nt
	global_load_dwordx4 v[164:167], v[0:1], off offset:3072 nt
	global_load_dwordx4 v[172:175], v[0:1], off offset:2048 nt
	v_add_u32_e32 v91, 0x19000, v193
	v_add_u32_e32 v212, 6, v2
	v_add_u32_e32 v208, 7, v2
	v_add_u32_e32 v3, 0x14800, v193
	v_add_u32_e32 v4, 0x15000, v193
	v_add_u32_e32 v8, 0x15800, v193
	v_add_u32_e32 v9, 0x16000, v193
	v_add_u32_e32 v10, 0x16800, v193
	v_add_u32_e32 v11, 0x17000, v193
	v_add_u32_e32 v28, 0x17800, v193
	v_add_u32_e32 v32, 0x18000, v193
	v_add_u32_e32 v36, 0x18800, v193
	v_ashrrev_i32_e32 v213, 31, v212
	v_ashrrev_i32_e32 v209, 31, v208
	ds_read_b128 v[64:67], v3
	ds_read_b128 v[0:3], v3 offset:16
	ds_read_b128 v[60:63], v4
	ds_read_b128 v[4:7], v4 offset:16
	ds_read_b128 v[92:95], v8
	ds_read_b128 v[12:15], v8 offset:16
	ds_read_b128 v[84:87], v9
	ds_read_b128 v[16:19], v9 offset:16
	ds_read_b128 v[80:83], v10
	ds_read_b128 v[20:23], v10 offset:16
	ds_read_b128 v[76:79], v11
	ds_read_b128 v[24:27], v11 offset:16
	ds_read_b128 v[72:75], v28
	ds_read_b128 v[28:31], v28 offset:16
	ds_read_b128 v[120:123], v32
	ds_read_b128 v[32:35], v32 offset:16
	ds_read_b128 v[68:71], v36
	ds_read_b128 v[36:39], v36 offset:16
	v_lshlrev_b64 v[8:9], 12, v[212:213]
	v_lshlrev_b64 v[10:11], 12, v[208:209]
	v_lshl_add_u64 v[8:9], v[198:199], 0, v[8:9]
	v_lshl_add_u64 v[10:11], v[198:199], 0, v[10:11]
	global_load_dwordx4 v[168:171], v[8:9], off nt
	global_load_dwordx4 v[160:163], v[8:9], off offset:1024 nt
	global_load_dwordx4 v[140:143], v[8:9], off offset:2048 nt
	global_load_dwordx4 v[136:139], v[8:9], off offset:3072 nt
	global_load_dwordx4 v[48:51], v[10:11], off nt
	global_load_dwordx4 v[44:47], v[10:11], off offset:1024 nt
	global_load_dwordx4 v[40:43], v[10:11], off offset:2048 nt
	s_nop 0
	global_load_dwordx4 v[8:11], v[10:11], off offset:3072 nt
	v_add_u32_e32 v106, 0x19800, v193
	v_lshlrev_b64 v[210:211], 11, v[210:211]
	v_lshlrev_b64 v[212:213], 11, v[212:213]
	v_lshl_add_u64 v[212:213], v[194:195], 0, v[212:213]
	s_waitcnt vmcnt(15)
	v_pk_mul_f32 v[52:53], v[190:191], v[190:191]
	v_pk_mul_f32 v[54:55], v[188:189], v[188:189]
	s_waitcnt vmcnt(14)
	v_pk_mul_f32 v[56:57], v[186:187], v[186:187]
	v_pk_mul_f32 v[58:59], v[184:185], v[184:185]
	v_pk_mov_b32 v[96:97], v[54:55], v[52:53] op_sel:[1,0]
	v_mov_b32_e32 v55, v53
	v_pk_mov_b32 v[52:53], v[58:59], v[56:57] op_sel:[1,0]
	v_mov_b32_e32 v59, v57
	s_waitcnt vmcnt(12)
	v_mul_f32_e32 v88, v181, v181
	v_mul_f32_e32 v90, v183, v183
	v_pk_add_f32 v[54:55], v[96:97], v[54:55]
	v_pk_add_f32 v[52:53], v[52:53], v[58:59]
	v_mul_f32_e32 v98, v176, v176
	v_mul_f32_e32 v99, v177, v177
	v_mul_f32_e32 v100, v178, v178
	v_mul_f32_e32 v101, v179, v179
	v_pk_fma_f32 v[56:57], v[180:181], v[180:181], v[88:89] op_sel_hi:[1,1,0]
	v_pk_fma_f32 v[88:89], v[182:183], v[182:183], v[90:91] op_sel_hi:[1,1,0]
	v_pk_add_f32 v[54:55], v[54:55], v[54:55] op_sel:[0,1] op_sel_hi:[1,0]
	v_pk_add_f32 v[52:53], v[52:53], v[52:53] op_sel:[0,1] op_sel_hi:[1,0]
	v_mov_b32_e32 v57, v100
	v_mov_b32_e32 v89, v101
	v_mov_b32_e32 v55, v98
	v_mov_b32_e32 v53, v99
	v_pk_add_f32 v[56:57], v[56:57], v[88:89]
	v_pk_add_f32 v[52:53], v[54:55], v[52:53]
	s_waitcnt vmcnt(11)
	v_pk_mul_f32 v[54:55], v[132:133], v[132:133]
	v_pk_add_f32 v[52:53], v[52:53], v[56:57]
	s_waitcnt vmcnt(10)
	v_pk_mul_f32 v[56:57], v[126:127], v[126:127]
	v_add_f32_e32 v88, v52, v53
	ds_bpermute_b32 v89, v217, v88
	v_pk_mul_f32 v[52:53], v[134:135], v[134:135]
	v_pk_mul_f32 v[58:59], v[124:125], v[124:125]
	s_waitcnt vmcnt(8)
	v_mul_f32_e32 v90, v175, v175
	v_mul_f32_e32 v98, v166, v166
	s_waitcnt lgkmcnt(0)
	v_add_f32_e32 v89, v88, v89
	ds_bpermute_b32 v96, v218, v89
	v_mul_f32_e32 v88, v173, v173
	v_mul_f32_e32 v99, v167, v167
	v_mul_f32_e32 v101, v164, v164
	v_mul_f32_e32 v102, v165, v165
	s_waitcnt lgkmcnt(0)
	v_add_f32_e32 v89, v89, v96
	ds_bpermute_b32 v100, v219, v89
	v_pk_mov_b32 v[96:97], v[54:55], v[52:53] op_sel:[1,0]
	v_mov_b32_e32 v55, v53
	v_pk_mov_b32 v[52:53], v[58:59], v[56:57] op_sel:[1,0]
	v_mov_b32_e32 v59, v57
	s_waitcnt lgkmcnt(0)
	v_add_f32_e32 v100, v89, v100
	ds_bpermute_b32 v103, v220, v100
	v_pk_fma_f32 v[56:57], v[172:173], v[172:173], v[88:89] op_sel_hi:[1,1,0]
	v_pk_fma_f32 v[88:89], v[174:175], v[174:175], v[90:91] op_sel_hi:[1,1,0]
	v_pk_add_f32 v[52:53], v[52:53], v[58:59]
	v_pk_add_f32 v[54:55], v[96:97], v[54:55]
	s_waitcnt lgkmcnt(0)
	v_add_f32_e32 v90, v100, v103
	ds_bpermute_b32 v100, v221, v90
	v_pk_add_f32 v[52:53], v[52:53], v[52:53] op_sel:[0,1] op_sel_hi:[1,0]
	v_pk_add_f32 v[54:55], v[54:55], v[54:55] op_sel:[0,1] op_sel_hi:[1,0]
	v_mov_b32_e32 v57, v98
	v_mov_b32_e32 v89, v99
	s_waitcnt lgkmcnt(0)
	v_add_f32_e32 v58, v90, v100
	ds_bpermute_b32 v59, v222, v58
	v_mov_b32_e32 v55, v101
	v_pk_add_f32 v[56:57], v[56:57], v[88:89]
	s_waitcnt vmcnt(7)
	v_pk_mul_f32 v[240:241], v[168:169], v[168:169]
	s_waitcnt lgkmcnt(0)
	v_add_f32_e32 v231, v58, v59
	v_fmamk_f32 v53, v231, 0x3a800000, v227
	v_mul_f32_e32 v58, 0x4b800000, v53
	v_cmp_gt_f32_e64 s[0:1], s19, v53
	s_nop 1
	v_cndmask_b32_e64 v53, v53, v58, s[0:1]
	v_rsq_f32_e32 v58, v53
	v_mov_b32_e32 v53, v102
	v_pk_add_f32 v[52:53], v[54:55], v[52:53]
	s_nop 0
	v_pk_add_f32 v[104:105], v[52:53], v[56:57]
	v_mul_f32_e32 v52, 0x45800000, v58
	v_add_f32_e32 v104, v104, v105
	ds_bpermute_b32 v105, v217, v104
	v_cndmask_b32_e64 v232, v58, v52, s[0:1]
	v_pk_mul_f32 v[234:235], v[188:189], v[232:233] op_sel_hi:[1,0]
	ds_read_b128 v[100:103], v91
	ds_read_b128 v[52:55], v91 offset:16
	ds_read_b128 v[96:99], v106
	ds_read_b128 v[56:59], v106 offset:16
	ds_read_b128 v[128:131], v225
	ds_read_b128 v[88:91], v225 offset:16
	ds_read_b128 v[156:159], v226
	ds_read_b128 v[116:119], v226 offset:16
	ds_read_b128 v[152:155], v228
	ds_read_b128 v[112:115], v228 offset:16
	s_waitcnt lgkmcnt(10)
	v_add_f32_e32 v233, v104, v105
	ds_bpermute_b32 v236, v218, v233
	ds_read_b128 v[148:151], v229
	ds_read_b128 v[108:111], v229 offset:16
	ds_read_b128 v[144:147], v230
	ds_read_b128 v[104:107], v230 offset:16
	v_cvt_pk_bf16_f32 v234, v234, v235
	s_waitcnt lgkmcnt(4)
	v_add_f32_e32 v233, v233, v236
	ds_bpermute_b32 v238, v219, v233
	v_pk_mul_f32 v[236:237], v[190:191], v[232:233] op_sel_hi:[1,0]
	s_waitcnt lgkmcnt(0)
	v_add_f32_e32 v233, v233, v238
	ds_bpermute_b32 v238, v220, v233
	v_cvt_pk_bf16_f32 v235, v236, v237
	global_store_dwordx2 v[204:205], v[234:235], off offset:-1024
	v_pk_mul_f32 v[234:235], v[184:185], v[232:233] op_sel_hi:[1,0]
	v_pk_mul_f32 v[236:237], v[186:187], v[232:233] op_sel_hi:[1,0]
	s_waitcnt lgkmcnt(0)
	v_add_f32_e32 v233, v233, v238
	ds_bpermute_b32 v238, v221, v233
	v_cvt_pk_bf16_f32 v234, v234, v235
	v_cvt_pk_bf16_f32 v235, v236, v237
	global_store_dwordx2 v[204:205], v[234:235], off offset:-512
	v_pk_mul_f32 v[234:235], v[180:181], v[232:233] op_sel_hi:[1,0]
	v_pk_mul_f32 v[236:237], v[182:183], v[232:233] op_sel_hi:[1,0]
	s_waitcnt lgkmcnt(0)
	v_add_f32_e32 v233, v233, v238
	ds_bpermute_b32 v238, v222, v233
	v_cvt_pk_bf16_f32 v234, v234, v235
	v_cvt_pk_bf16_f32 v235, v236, v237
	global_store_dwordx2 v[204:205], v[234:235], off
	v_pk_mul_f32 v[234:235], v[178:179], v[232:233] op_sel_hi:[1,0]
	v_pk_mul_f32 v[236:237], v[176:177], v[232:233] op_sel_hi:[1,0]
	s_waitcnt lgkmcnt(0)
	v_add_f32_e32 v232, v233, v238
	v_fmamk_f32 v233, v232, 0x3a800000, v227
	v_mul_f32_e32 v238, 0x4b800000, v233
	v_cmp_gt_f32_e64 s[0:1], s19, v233
	v_cvt_pk_bf16_f32 v236, v236, v237
	v_cvt_pk_bf16_f32 v237, v234, v235
	global_store_dwordx2 v[204:205], v[236:237], off offset:512
	s_nop 0
	v_cndmask_b32_e64 v233, v233, v238, s[0:1]
	v_pk_mul_f32 v[238:239], v[170:171], v[170:171]
	v_rsq_f32_e32 v233, v233
	v_pk_mov_b32 v[242:243], v[240:241], v[238:239] op_sel:[1,0]
	v_mov_b32_e32 v241, v239
	v_pk_add_f32 v[238:239], v[242:243], v[240:241]
	s_waitcnt vmcnt(10)
	v_pk_mul_f32 v[240:241], v[162:163], v[162:163]
	v_pk_mul_f32 v[242:243], v[160:161], v[160:161]
	v_pk_add_f32 v[238:239], v[238:239], v[238:239] op_sel:[0,1] op_sel_hi:[1,0]
	v_pk_mov_b32 v[244:245], v[242:243], v[240:241] op_sel:[1,0]
	v_mov_b32_e32 v243, v241
	v_pk_add_f32 v[240:241], v[244:245], v[242:243]
	s_waitcnt vmcnt(8)
	v_mul_f32_e32 v239, v136, v136
	v_pk_add_f32 v[240:241], v[240:241], v[240:241] op_sel:[0,1] op_sel_hi:[1,0]
	v_mul_f32_e32 v242, v143, v143
	v_mul_f32_e32 v241, v137, v137
	v_pk_add_f32 v[238:239], v[238:239], v[240:241]
	v_mul_f32_e32 v240, v141, v141
	v_pk_fma_f32 v[240:241], v[140:141], v[140:141], v[240:241] op_sel_hi:[1,1,0]
	v_pk_fma_f32 v[242:243], v[142:143], v[142:143], v[242:243] op_sel_hi:[1,1,0]
	v_mul_f32_e32 v241, v138, v138
	v_mul_f32_e32 v243, v139, v139
	v_pk_add_f32 v[240:241], v[240:241], v[242:243]
	v_mul_f32_e32 v234, 0x45800000, v233
	v_pk_add_f32 v[238:239], v[238:239], v[240:241]
	v_cndmask_b32_e64 v234, v233, v234, s[0:1]
	v_add_f32_e32 v238, v238, v239
	ds_bpermute_b32 v239, v217, v238
	s_waitcnt lgkmcnt(0)
	v_add_f32_e32 v235, v238, v239
	ds_bpermute_b32 v240, v218, v235
	v_pk_mul_f32 v[236:237], v[132:133], v[234:235] op_sel_hi:[1,0]
	v_pk_mul_f32 v[238:239], v[134:135], v[234:235] op_sel_hi:[1,0]
	v_cvt_pk_bf16_f32 v236, v236, v237
	s_waitcnt lgkmcnt(0)
	v_add_f32_e32 v233, v235, v240
	ds_bpermute_b32 v235, v219, v233
	v_cvt_pk_bf16_f32 v237, v238, v239
	v_lshl_add_u64 v[238:239], v[194:195], 0, v[210:211]
	global_store_dwordx2 v[238:239], v[236:237], off
	s_waitcnt lgkmcnt(0)
	v_add_f32_e32 v233, v233, v235
	ds_bpermute_b32 v235, v220, v233
	s_waitcnt lgkmcnt(0)
	v_add_f32_e32 v233, v233, v235
	v_pk_mul_f32 v[210:211], v[124:125], v[234:235] op_sel_hi:[1,0]
	v_pk_mul_f32 v[236:237], v[126:127], v[234:235] op_sel_hi:[1,0]
	ds_bpermute_b32 v235, v221, v233
	v_cvt_pk_bf16_f32 v210, v210, v211
	v_cvt_pk_bf16_f32 v211, v236, v237
	global_store_dwordx2 v[238:239], v[210:211], off offset:512
	s_waitcnt lgkmcnt(0)
	v_add_f32_e32 v233, v233, v235
	ds_bpermute_b32 v240, v222, v233
	v_pk_mul_f32 v[210:211], v[172:173], v[234:235] op_sel_hi:[1,0]
	v_pk_mul_f32 v[236:237], v[174:175], v[234:235] op_sel_hi:[1,0]
	v_cvt_pk_bf16_f32 v210, v210, v211
	s_nop 0
	v_cvt_pk_bf16_f32 v211, v236, v237
	global_store_dwordx2 v[238:239], v[210:211], off offset:1024
	s_waitcnt lgkmcnt(0)
	v_add_f32_e32 v210, v233, v240
	v_fmamk_f32 v211, v210, 0x3a800000, v227
	v_mul_f32_e32 v233, 0x4b800000, v211
	v_cmp_gt_f32_e64 s[0:1], s19, v211
	v_pk_mul_f32 v[236:237], v[166:167], v[234:235] op_sel_hi:[1,0]
	v_pk_mul_f32 v[234:235], v[164:165], v[234:235] op_sel_hi:[1,0]
	v_cndmask_b32_e64 v211, v211, v233, s[0:1]
	v_rsq_f32_e32 v211, v211
	v_cvt_pk_bf16_f32 v234, v234, v235
	v_cvt_pk_bf16_f32 v235, v236, v237
	global_store_dwordx2 v[238:239], v[234:235], off offset:1536
	v_mul_f32_e32 v233, 0x45800000, v211
	v_cndmask_b32_e64 v234, v211, v233, s[0:1]
	v_pk_mul_f32 v[236:237], v[168:169], v[234:235] op_sel_hi:[1,0]
	v_pk_mul_f32 v[238:239], v[170:171], v[234:235] op_sel_hi:[1,0]
	v_cvt_pk_bf16_f32 v236, v236, v237
	v_fma_f32 v211, v188, v128, 0
	v_cvt_pk_bf16_f32 v237, v238, v239
	global_store_dwordx2 v[212:213], v[236:237], off
	v_pk_mul_f32 v[236:237], v[160:161], v[234:235] op_sel_hi:[1,0]
	v_pk_mul_f32 v[238:239], v[162:163], v[234:235] op_sel_hi:[1,0]
	v_cvt_pk_bf16_f32 v236, v236, v237
	v_fma_f32 v233, v188, v131, 0
	v_cvt_pk_bf16_f32 v237, v238, v239
	global_store_dwordx2 v[212:213], v[236:237], off offset:512
	v_pk_mul_f32 v[236:237], v[140:141], v[234:235] op_sel_hi:[1,0]
	v_pk_mul_f32 v[238:239], v[142:143], v[234:235] op_sel_hi:[1,0]
	v_cvt_pk_bf16_f32 v236, v236, v237
	v_fmac_f32_e32 v211, v189, v156
	v_cvt_pk_bf16_f32 v237, v238, v239
	global_store_dwordx2 v[212:213], v[236:237], off offset:1024
	v_pk_mul_f32 v[236:237], v[138:139], v[234:235] op_sel_hi:[1,0]
	v_pk_mul_f32 v[234:235], v[136:137], v[234:235] op_sel_hi:[1,0]
	v_fmac_f32_e32 v233, v189, v159
	v_cvt_pk_bf16_f32 v234, v234, v235
	v_cvt_pk_bf16_f32 v235, v236, v237
	global_store_dwordx2 v[212:213], v[234:235], off offset:1536
	v_fma_f32 v212, v188, v129, 0
	v_fma_f32 v213, v188, v130, 0
	v_fma_f32 v234, v188, v88, 0
	v_fma_f32 v235, v188, v89, 0
	v_fma_f32 v236, v188, v90, 0
	v_fma_f32 v188, v188, v91, 0
	v_fmac_f32_e32 v212, v189, v157
	v_fmac_f32_e32 v213, v189, v158
	v_fmac_f32_e32 v234, v189, v116
	v_fmac_f32_e32 v235, v189, v117
	v_fmac_f32_e32 v236, v189, v118
	v_fmac_f32_e32 v188, v189, v119
	v_fmac_f32_e32 v211, v190, v152
	v_fmac_f32_e32 v212, v190, v153
	v_fmac_f32_e32 v213, v190, v154
	v_fmac_f32_e32 v233, v190, v155
	v_fmac_f32_e32 v234, v190, v112
	v_fmac_f32_e32 v235, v190, v113
	v_fmac_f32_e32 v236, v190, v114
	v_fmac_f32_e32 v188, v190, v115
	v_fmac_f32_e32 v211, v191, v148
	v_fmac_f32_e32 v212, v191, v149
	v_fmac_f32_e32 v213, v191, v150
	v_fmac_f32_e32 v233, v191, v151
	v_fmac_f32_e32 v234, v191, v108
	v_fmac_f32_e32 v235, v191, v109
	v_fmac_f32_e32 v236, v191, v110
	v_fmac_f32_e32 v188, v191, v111
	v_fmac_f32_e32 v211, v184, v144
	v_fmac_f32_e32 v212, v184, v145
	v_fmac_f32_e32 v213, v184, v146
	v_fmac_f32_e32 v233, v184, v147
	v_fmac_f32_e32 v234, v184, v104
	v_fmac_f32_e32 v235, v184, v105
	v_fmac_f32_e32 v236, v184, v106
	v_fmac_f32_e32 v188, v184, v107
	v_fmac_f32_e32 v211, v185, v64
	v_fmac_f32_e32 v212, v185, v65
	v_fmac_f32_e32 v213, v185, v66
	v_fmac_f32_e32 v233, v185, v67
	v_fmac_f32_e32 v234, v185, v0
	v_fmac_f32_e32 v235, v185, v1
	v_fmac_f32_e32 v236, v185, v2
	v_fmac_f32_e32 v188, v185, v3
	v_fmac_f32_e32 v211, v186, v60
	v_fmac_f32_e32 v212, v186, v61
	v_fmac_f32_e32 v213, v186, v62
	v_fmac_f32_e32 v233, v186, v63
	v_fmac_f32_e32 v234, v186, v4
	v_fmac_f32_e32 v235, v186, v5
	v_fmac_f32_e32 v236, v186, v6
	v_fmac_f32_e32 v188, v186, v7
	v_fmac_f32_e32 v211, v187, v92
	v_fmac_f32_e32 v212, v187, v93
	v_fmac_f32_e32 v213, v187, v94
	v_fmac_f32_e32 v233, v187, v95
	v_fmac_f32_e32 v234, v187, v12
	v_fmac_f32_e32 v235, v187, v13
	v_fmac_f32_e32 v236, v187, v14
	v_fmac_f32_e32 v188, v187, v15
	v_fmac_f32_e32 v211, v180, v84
	v_fmac_f32_e32 v212, v180, v85
	v_fmac_f32_e32 v213, v180, v86
	v_fmac_f32_e32 v233, v180, v87
	v_fmac_f32_e32 v234, v180, v16
	v_fmac_f32_e32 v235, v180, v17
	v_fmac_f32_e32 v236, v180, v18
	v_fmac_f32_e32 v188, v180, v19
	v_fmac_f32_e32 v211, v181, v80
	v_fmac_f32_e32 v212, v181, v81
	v_fmac_f32_e32 v213, v181, v82
	v_fmac_f32_e32 v233, v181, v83
	v_fmac_f32_e32 v234, v181, v20
	v_fmac_f32_e32 v235, v181, v21
	v_fmac_f32_e32 v236, v181, v22
	v_fmac_f32_e32 v188, v181, v23
	v_fmac_f32_e32 v211, v182, v76
	v_fmac_f32_e32 v212, v182, v77
	v_fmac_f32_e32 v213, v182, v78
	v_fmac_f32_e32 v233, v182, v79
	v_fmac_f32_e32 v234, v182, v24
	v_fmac_f32_e32 v235, v182, v25
	v_fmac_f32_e32 v236, v182, v26
	v_fmac_f32_e32 v188, v182, v27
	v_fmac_f32_e32 v211, v183, v72
	v_fmac_f32_e32 v212, v183, v73
	v_fmac_f32_e32 v213, v183, v74
	v_fmac_f32_e32 v233, v183, v75
	v_fmac_f32_e32 v234, v183, v28
	v_fmac_f32_e32 v235, v183, v29
	v_fmac_f32_e32 v236, v183, v30
	v_fmac_f32_e32 v188, v183, v31
	v_fmac_f32_e32 v211, v176, v120
	v_fmac_f32_e32 v212, v176, v121
	v_fmac_f32_e32 v213, v176, v122
	v_fmac_f32_e32 v233, v176, v123
	v_fmac_f32_e32 v234, v176, v32
	v_fmac_f32_e32 v235, v176, v33
	v_fmac_f32_e32 v236, v176, v34
	v_fmac_f32_e32 v188, v176, v35
	v_fmac_f32_e32 v211, v177, v68
	v_fmac_f32_e32 v212, v177, v69
	v_fmac_f32_e32 v213, v177, v70
	v_fmac_f32_e32 v233, v177, v71
	v_fmac_f32_e32 v234, v177, v36
	v_fmac_f32_e32 v235, v177, v37
	v_fmac_f32_e32 v236, v177, v38
	v_fmac_f32_e32 v188, v177, v39
	v_fmac_f32_e32 v211, v178, v100
	v_fmac_f32_e32 v212, v178, v101
	v_fmac_f32_e32 v213, v178, v102
	v_fmac_f32_e32 v233, v178, v103
	v_fmac_f32_e32 v234, v178, v52
	v_fmac_f32_e32 v235, v178, v53
	v_fmac_f32_e32 v236, v178, v54
	v_fmac_f32_e32 v188, v178, v55
	v_fmac_f32_e32 v211, v179, v96
	v_fmac_f32_e32 v212, v179, v97
	v_fmac_f32_e32 v213, v179, v98
	v_fmac_f32_e32 v233, v179, v99
	v_fmac_f32_e32 v234, v179, v56
	v_fmac_f32_e32 v235, v179, v57
	v_fmac_f32_e32 v236, v179, v58
	v_fmac_f32_e32 v188, v179, v59
	v_fma_f32 v176, v132, v128, 0
	v_fma_f32 v177, v132, v129, 0
	v_fma_f32 v178, v132, v130, 0
	v_fma_f32 v179, v132, v131, 0
	v_fma_f32 v180, v132, v88, 0
	v_fma_f32 v181, v132, v89, 0
	v_fma_f32 v182, v132, v90, 0
	v_fma_f32 v132, v132, v91, 0
	v_fmac_f32_e32 v176, v133, v156
	v_fmac_f32_e32 v177, v133, v157
	v_fmac_f32_e32 v178, v133, v158
	v_fmac_f32_e32 v179, v133, v159
	v_fmac_f32_e32 v180, v133, v116
	v_fmac_f32_e32 v181, v133, v117
	v_fmac_f32_e32 v182, v133, v118
	v_fmac_f32_e32 v132, v133, v119
	v_fmac_f32_e32 v176, v134, v152
	v_fmac_f32_e32 v177, v134, v153
	v_fmac_f32_e32 v178, v134, v154
	v_fmac_f32_e32 v179, v134, v155
	v_fmac_f32_e32 v180, v134, v112
	v_fmac_f32_e32 v181, v134, v113
	v_fmac_f32_e32 v182, v134, v114
	v_fmac_f32_e32 v132, v134, v115
	v_fmac_f32_e32 v176, v135, v148
	v_fmac_f32_e32 v177, v135, v149
	v_fmac_f32_e32 v178, v135, v150
	v_fmac_f32_e32 v179, v135, v151
	v_fmac_f32_e32 v180, v135, v108
	v_fmac_f32_e32 v181, v135, v109
	v_fmac_f32_e32 v182, v135, v110
	v_fmac_f32_e32 v132, v135, v111
	v_fmac_f32_e32 v176, v124, v144
	v_fmac_f32_e32 v177, v124, v145
	v_fmac_f32_e32 v178, v124, v146
	v_fmac_f32_e32 v179, v124, v147
	v_fmac_f32_e32 v180, v124, v104
	v_fmac_f32_e32 v181, v124, v105
	v_fmac_f32_e32 v182, v124, v106
	v_fmac_f32_e32 v132, v124, v107
	v_fmac_f32_e32 v176, v125, v64
	v_fmac_f32_e32 v177, v125, v65
	v_fmac_f32_e32 v178, v125, v66
	v_fmac_f32_e32 v179, v125, v67
	v_fmac_f32_e32 v180, v125, v0
	v_fmac_f32_e32 v181, v125, v1
	v_fmac_f32_e32 v182, v125, v2
	v_fmac_f32_e32 v132, v125, v3
	v_fmac_f32_e32 v176, v126, v60
	v_fmac_f32_e32 v177, v126, v61
	v_fmac_f32_e32 v178, v126, v62
	v_fmac_f32_e32 v179, v126, v63
	v_fmac_f32_e32 v180, v126, v4
	v_fmac_f32_e32 v181, v126, v5
	v_fmac_f32_e32 v182, v126, v6
	v_fmac_f32_e32 v132, v126, v7
	v_fmac_f32_e32 v176, v127, v92
	v_fmac_f32_e32 v177, v127, v93
	v_fmac_f32_e32 v178, v127, v94
	v_fmac_f32_e32 v179, v127, v95
	v_fmac_f32_e32 v180, v127, v12
	v_fmac_f32_e32 v181, v127, v13
	v_fmac_f32_e32 v182, v127, v14
	v_fmac_f32_e32 v132, v127, v15
	v_fma_f32 v124, v168, v128, 0
	v_fma_f32 v125, v168, v129, 0
	v_fma_f32 v126, v168, v130, 0
	v_fma_f32 v127, v168, v131, 0
	s_waitcnt vmcnt(15)
	v_fma_f32 v128, v48, v128, 0
	v_fma_f32 v129, v48, v129, 0
	v_fma_f32 v130, v48, v130, 0
	v_fma_f32 v131, v48, v131, 0
	v_fmac_f32_e32 v124, v169, v156
	v_fmac_f32_e32 v125, v169, v157
	v_fmac_f32_e32 v126, v169, v158
	v_fmac_f32_e32 v127, v169, v159
	v_fmac_f32_e32 v128, v49, v156
	v_fmac_f32_e32 v129, v49, v157
	v_fmac_f32_e32 v130, v49, v158
	v_fmac_f32_e32 v131, v49, v159
	v_fmac_f32_e32 v124, v170, v152
	v_fmac_f32_e32 v125, v170, v153
	v_fmac_f32_e32 v126, v170, v154
	v_fmac_f32_e32 v127, v170, v155
	v_fmac_f32_e32 v128, v50, v152
	v_fmac_f32_e32 v129, v50, v153
	v_fmac_f32_e32 v130, v50, v154
	v_fmac_f32_e32 v131, v50, v155
	v_fmac_f32_e32 v124, v171, v148
	v_fmac_f32_e32 v125, v171, v149
	v_fmac_f32_e32 v126, v171, v150
	v_fmac_f32_e32 v127, v171, v151
	v_fmac_f32_e32 v128, v51, v148
	v_fmac_f32_e32 v129, v51, v149
	v_fmac_f32_e32 v130, v51, v150
	v_fmac_f32_e32 v131, v51, v151
	v_fmac_f32_e32 v124, v160, v144
	v_fmac_f32_e32 v125, v160, v145
	v_fmac_f32_e32 v126, v160, v146
	v_fmac_f32_e32 v127, v160, v147
	s_waitcnt vmcnt(14)
	v_fmac_f32_e32 v128, v44, v144
	v_fmac_f32_e32 v129, v44, v145
	v_fmac_f32_e32 v130, v44, v146
	v_fmac_f32_e32 v131, v44, v147
	v_fmac_f32_e32 v124, v161, v64
	v_fmac_f32_e32 v125, v161, v65
	v_fmac_f32_e32 v126, v161, v66
	v_fmac_f32_e32 v127, v161, v67
	v_fmac_f32_e32 v128, v45, v64
	v_fmac_f32_e32 v129, v45, v65
	v_fmac_f32_e32 v130, v45, v66
	v_fmac_f32_e32 v131, v45, v67
	v_fmac_f32_e32 v124, v162, v60
	v_fmac_f32_e32 v125, v162, v61
	v_fmac_f32_e32 v126, v162, v62
	v_fmac_f32_e32 v127, v162, v63
	v_fmac_f32_e32 v128, v46, v60
	v_fmac_f32_e32 v129, v46, v61
	v_fmac_f32_e32 v130, v46, v62
	v_fmac_f32_e32 v131, v46, v63
	v_pk_mul_f32 v[60:61], v[50:51], v[50:51]
	v_pk_mul_f32 v[62:63], v[48:49], v[48:49]
	v_fmac_f32_e32 v124, v163, v92
	v_pk_mov_b32 v[64:65], v[62:63], v[60:61] op_sel:[1,0]
	v_mov_b32_e32 v63, v61
	v_pk_add_f32 v[60:61], v[64:65], v[62:63]
	v_pk_mul_f32 v[62:63], v[46:47], v[46:47]
	v_pk_mul_f32 v[64:65], v[44:45], v[44:45]
	v_pk_add_f32 v[60:61], v[60:61], v[60:61] op_sel:[0,1] op_sel_hi:[1,0]
	v_pk_mov_b32 v[66:67], v[64:65], v[62:63] op_sel:[1,0]
	v_mov_b32_e32 v65, v63
	v_pk_add_f32 v[62:63], v[66:67], v[64:65]
	s_waitcnt vmcnt(12)
	v_mul_f32_e32 v61, v8, v8
	v_pk_add_f32 v[62:63], v[62:63], v[62:63] op_sel:[0,1] op_sel_hi:[1,0]
	v_mul_f32_e32 v64, v43, v43
	v_mul_f32_e32 v63, v9, v9
	v_pk_add_f32 v[60:61], v[60:61], v[62:63]
	v_mul_f32_e32 v62, v41, v41
	v_pk_fma_f32 v[62:63], v[40:41], v[40:41], v[62:63] op_sel_hi:[1,1,0]
	v_pk_fma_f32 v[64:65], v[42:43], v[42:43], v[64:65] op_sel_hi:[1,1,0]
	v_mul_f32_e32 v63, v10, v10
	v_mul_f32_e32 v65, v11, v11
	v_pk_add_f32 v[62:63], v[62:63], v[64:65]
	v_fmac_f32_e32 v128, v47, v92
	v_pk_add_f32 v[60:61], v[60:61], v[62:63]
	v_fmac_f32_e32 v176, v172, v84
	v_add_f32_e32 v60, v60, v61
	ds_bpermute_b32 v61, v217, v60
	v_fmac_f32_e32 v177, v172, v85
	v_fmac_f32_e32 v178, v172, v86
	v_fmac_f32_e32 v179, v172, v87
	v_fmac_f32_e32 v180, v172, v16
	s_waitcnt lgkmcnt(0)
	v_add_f32_e32 v60, v60, v61
	ds_bpermute_b32 v61, v218, v60
	v_fmac_f32_e32 v181, v172, v17
	v_fmac_f32_e32 v182, v172, v18
	v_fmac_f32_e32 v132, v172, v19
	v_fmac_f32_e32 v124, v140, v84
	s_waitcnt lgkmcnt(0)
	v_add_f32_e32 v60, v60, v61
	ds_bpermute_b32 v61, v219, v60
	v_fmac_f32_e32 v128, v40, v84
	v_fmac_f32_e32 v176, v173, v80
	v_fmac_f32_e32 v177, v173, v81
	v_fmac_f32_e32 v178, v173, v82
	s_waitcnt lgkmcnt(0)
	v_add_f32_e32 v60, v60, v61
	ds_bpermute_b32 v61, v220, v60
	v_fmac_f32_e32 v179, v173, v83
	v_fmac_f32_e32 v180, v173, v20
	v_fmac_f32_e32 v181, v173, v21
	v_fmac_f32_e32 v182, v173, v22
	s_waitcnt lgkmcnt(0)
	v_add_f32_e32 v60, v60, v61
	ds_bpermute_b32 v61, v221, v60
	v_fmac_f32_e32 v132, v173, v23
	v_fma_f32 v133, v168, v88, 0
	v_fmac_f32_e32 v124, v141, v80
	v_fmac_f32_e32 v128, v41, v80
	s_waitcnt lgkmcnt(0)
	v_add_f32_e32 v60, v60, v61
	ds_bpermute_b32 v61, v222, v60
	v_fmac_f32_e32 v176, v174, v76
	v_fmac_f32_e32 v177, v174, v77
	v_fmac_f32_e32 v178, v174, v78
	v_fmac_f32_e32 v179, v174, v79
	s_waitcnt lgkmcnt(0)
	v_add_f32_e32 v60, v60, v61
	v_fmamk_f32 v61, v60, 0x3a800000, v227
	v_mul_f32_e32 v62, 0x4b800000, v61
	v_cmp_gt_f32_e64 s[0:1], s19, v61
	v_fmac_f32_e32 v180, v174, v24
	v_fmac_f32_e32 v181, v174, v25
	v_cndmask_b32_e64 v61, v61, v62, s[0:1]
	v_fmac_f32_e32 v182, v174, v26
	v_fmac_f32_e32 v132, v174, v27
	v_fmac_f32_e32 v133, v169, v116
	v_fma_f32 v134, v168, v89, 0
	v_fmac_f32_e32 v124, v142, v76
	v_fmac_f32_e32 v128, v42, v76
	v_rsq_f32_e32 v61, v61
	v_fmac_f32_e32 v176, v175, v72
	v_fmac_f32_e32 v177, v175, v73
	v_fmac_f32_e32 v178, v175, v74
	v_fmac_f32_e32 v179, v175, v75
	v_fmac_f32_e32 v180, v175, v28
	v_fmac_f32_e32 v181, v175, v29
	v_fmac_f32_e32 v182, v175, v30
	v_fmac_f32_e32 v132, v175, v31
	v_fmac_f32_e32 v133, v170, v112
	v_fmac_f32_e32 v134, v169, v117
	v_fma_f32 v135, v168, v90, 0
	v_fmac_f32_e32 v124, v143, v72
	v_fmac_f32_e32 v128, v43, v72
	v_fmac_f32_e32 v176, v164, v120
	v_fmac_f32_e32 v177, v164, v121
	v_fmac_f32_e32 v178, v164, v122
	v_fmac_f32_e32 v179, v164, v123
	v_fmac_f32_e32 v180, v164, v32
	v_fmac_f32_e32 v181, v164, v33
	v_fmac_f32_e32 v182, v164, v34
	v_fmac_f32_e32 v132, v164, v35
	v_fmac_f32_e32 v133, v171, v108
	v_fmac_f32_e32 v134, v170, v113
	v_fmac_f32_e32 v135, v169, v118
	v_fma_f32 v164, v168, v91, 0
	v_fmac_f32_e32 v124, v136, v120
	v_fmac_f32_e32 v128, v8, v120
	v_fma_f32 v63, v48, v88, 0
	v_fmac_f32_e32 v176, v165, v68
	v_fmac_f32_e32 v134, v171, v109
	v_fmac_f32_e32 v135, v170, v114
	v_fmac_f32_e32 v164, v169, v119
	v_fmac_f32_e32 v125, v163, v93
	v_fmac_f32_e32 v133, v160, v104
	v_fmac_f32_e32 v124, v137, v68
	v_fmac_f32_e32 v128, v9, v68
	v_fma_f32 v66, v48, v89, 0
	v_fma_f32 v67, v48, v90, 0
	v_fma_f32 v68, v48, v91, 0
	v_fmac_f32_e32 v63, v49, v116
	v_fmac_f32_e32 v135, v171, v110
	v_fmac_f32_e32 v164, v170, v115
	v_fmac_f32_e32 v126, v163, v94
	v_fmac_f32_e32 v133, v161, v0
	v_fmac_f32_e32 v134, v160, v105
	v_fmac_f32_e32 v125, v140, v85
	v_fmac_f32_e32 v66, v49, v117
	v_fmac_f32_e32 v67, v49, v118
	v_fmac_f32_e32 v68, v49, v119
	v_fmac_f32_e32 v63, v50, v112
	v_mul_f32_e32 v62, 0x45800000, v61
	v_fmac_f32_e32 v164, v171, v111
	v_fmac_f32_e32 v127, v163, v95
	v_fmac_f32_e32 v133, v162, v4
	v_fmac_f32_e32 v134, v161, v1
	v_fmac_f32_e32 v135, v160, v106
	v_fmac_f32_e32 v125, v141, v81
	v_fmac_f32_e32 v126, v140, v86
	v_fmac_f32_e32 v66, v50, v113
	v_fmac_f32_e32 v67, v50, v114
	v_fmac_f32_e32 v68, v50, v115
	v_fmac_f32_e32 v63, v51, v108
	v_cndmask_b32_e64 v62, v61, v62, s[0:1]
	v_fmac_f32_e32 v133, v163, v12
	v_fmac_f32_e32 v134, v162, v5
	v_fmac_f32_e32 v135, v161, v2
	v_fmac_f32_e32 v164, v160, v107
	v_fmac_f32_e32 v125, v142, v77
	v_fmac_f32_e32 v126, v141, v82
	v_fmac_f32_e32 v127, v140, v87
	v_fmac_f32_e32 v66, v51, v109
	v_fmac_f32_e32 v67, v51, v110
	v_fmac_f32_e32 v68, v51, v111
	v_pk_mul_f32 v[50:51], v[50:51], v[62:63] op_sel_hi:[1,0]
	v_pk_mul_f32 v[48:49], v[48:49], v[62:63] op_sel_hi:[1,0]
	v_fmac_f32_e32 v134, v163, v13
	v_fmac_f32_e32 v135, v162, v6
	v_fmac_f32_e32 v164, v161, v3
	v_fmac_f32_e32 v125, v143, v73
	v_fmac_f32_e32 v126, v142, v78
	v_fmac_f32_e32 v127, v141, v83
	v_fmac_f32_e32 v133, v140, v16
	v_cvt_pk_bf16_f32 v48, v48, v49
	v_cvt_pk_bf16_f32 v49, v50, v51
	v_lshlrev_b64 v[50:51], 11, v[208:209]
	v_fmac_f32_e32 v135, v163, v14
	v_fmac_f32_e32 v164, v162, v7
	v_fmac_f32_e32 v126, v143, v74
	v_fmac_f32_e32 v127, v142, v79
	v_fmac_f32_e32 v133, v141, v20
	v_fmac_f32_e32 v134, v140, v17
	v_fmac_f32_e32 v125, v136, v121
	v_lshl_add_u64 v[50:51], v[194:195], 0, v[50:51]
	v_fmac_f32_e32 v164, v163, v15
	v_fmac_f32_e32 v127, v143, v75
	v_fmac_f32_e32 v133, v142, v24
	v_fmac_f32_e32 v134, v141, v21
	v_fmac_f32_e32 v135, v140, v18
	v_fmac_f32_e32 v124, v138, v100
	v_fmac_f32_e32 v125, v137, v69
	v_fmac_f32_e32 v126, v136, v122
	global_store_dwordx2 v[50:51], v[48:49], off
	v_pk_mul_f32 v[48:49], v[44:45], v[62:63] op_sel_hi:[1,0]
	v_fmac_f32_e32 v133, v143, v28
	v_fmac_f32_e32 v134, v142, v25
	v_fmac_f32_e32 v135, v141, v22
	v_fmac_f32_e32 v164, v140, v19
	v_fmac_f32_e32 v124, v139, v96
	v_fmac_f32_e32 v125, v138, v101
	v_fmac_f32_e32 v126, v137, v70
	v_fmac_f32_e32 v127, v136, v123
	v_cvt_pk_bf16_f32 v48, v48, v49
	v_pk_mul_f32 v[64:65], v[46:47], v[62:63] op_sel_hi:[1,0]
	v_fmac_f32_e32 v63, v44, v104
	v_cvt_pk_bf16_f32 v49, v64, v65
	v_fmac_f32_e32 v134, v143, v29
	v_fmac_f32_e32 v135, v142, v26
	v_fmac_f32_e32 v164, v141, v23
	v_fmac_f32_e32 v125, v139, v97
	v_fmac_f32_e32 v126, v138, v102
	v_fmac_f32_e32 v127, v137, v71
	v_fmac_f32_e32 v133, v136, v32
	v_fmac_f32_e32 v129, v47, v93
	global_store_dwordx2 v[50:51], v[48:49], off offset:512
	v_fmac_f32_e32 v66, v44, v105
	v_pk_mul_f32 v[48:49], v[42:43], v[62:63] op_sel_hi:[1,0]
	v_pk_mul_f32 v[64:65], v[40:41], v[62:63] op_sel_hi:[1,0]
	v_fmac_f32_e32 v63, v45, v0
	v_cndmask_b32_e64 v0, v211, v124, s[6:7]
	v_fmac_f32_e32 v135, v143, v30
	v_fmac_f32_e32 v164, v142, v27
	v_fmac_f32_e32 v126, v139, v98
	v_fmac_f32_e32 v127, v138, v103
	v_fmac_f32_e32 v133, v137, v36
	v_fmac_f32_e32 v134, v136, v33
	v_fmac_f32_e32 v130, v47, v94
	v_fmac_f32_e32 v129, v40, v85
	v_fmac_f32_e32 v67, v44, v106
	v_fmac_f32_e32 v66, v45, v1
	ds_bpermute_b32 v0, v222, v0
	v_cndmask_b32_e64 v1, v212, v125, s[6:7]
	v_fmac_f32_e32 v164, v143, v31
	v_fmac_f32_e32 v127, v139, v99
	v_fmac_f32_e32 v133, v138, v52
	v_fmac_f32_e32 v134, v137, v37
	v_fmac_f32_e32 v135, v136, v34
	v_fmac_f32_e32 v131, v47, v95
	v_fmac_f32_e32 v130, v40, v86
	v_fmac_f32_e32 v129, v41, v81
	v_fmac_f32_e32 v68, v44, v107
	v_fmac_f32_e32 v63, v46, v4
	v_fmac_f32_e32 v67, v45, v2
	ds_bpermute_b32 v1, v222, v1
	v_cndmask_b32_e64 v2, v213, v126, s[6:7]
	v_fmac_f32_e32 v133, v139, v56
	v_fmac_f32_e32 v134, v138, v53
	v_fmac_f32_e32 v135, v137, v38
	v_fmac_f32_e32 v164, v136, v35
	v_fmac_f32_e32 v131, v40, v87
	v_fmac_f32_e32 v130, v41, v82
	v_fmac_f32_e32 v129, v42, v77
	v_fmac_f32_e32 v63, v47, v12
	v_fmac_f32_e32 v66, v46, v5
	v_fmac_f32_e32 v68, v45, v3
	ds_bpermute_b32 v2, v222, v2
	v_cndmask_b32_e64 v3, v233, v127, s[6:7]
	v_fmac_f32_e32 v134, v139, v57
	v_fmac_f32_e32 v135, v138, v54
	v_fmac_f32_e32 v164, v137, v39
	v_fmac_f32_e32 v131, v41, v83
	v_fmac_f32_e32 v130, v42, v78
	v_fmac_f32_e32 v129, v43, v73
	v_fmac_f32_e32 v63, v40, v16
	v_fmac_f32_e32 v66, v47, v13
	v_fmac_f32_e32 v67, v46, v6
	ds_bpermute_b32 v3, v222, v3
	v_cndmask_b32_e64 v4, v234, v133, s[6:7]
	v_fmac_f32_e32 v135, v139, v58
	v_fmac_f32_e32 v164, v138, v55
	v_fmac_f32_e32 v131, v42, v79
	v_fmac_f32_e32 v130, v43, v74
	v_fmac_f32_e32 v129, v8, v121
	v_fmac_f32_e32 v63, v41, v20
	v_fmac_f32_e32 v66, v40, v17
	v_fmac_f32_e32 v67, v47, v14
	v_fmac_f32_e32 v68, v46, v7
	ds_bpermute_b32 v4, v222, v4
	v_cndmask_b32_e64 v5, v235, v134, s[6:7]
	v_cndmask_b32_e64 v20, v124, v211, s[6:7]
	v_fmac_f32_e32 v176, v166, v100
	v_fmac_f32_e32 v177, v165, v69
	v_fmac_f32_e32 v164, v139, v59
	v_fmac_f32_e32 v131, v43, v75
	v_fmac_f32_e32 v130, v8, v122
	v_fmac_f32_e32 v129, v9, v69
	v_fmac_f32_e32 v128, v10, v100
	v_fmac_f32_e32 v63, v42, v24
	v_fmac_f32_e32 v66, v41, v21
	v_fmac_f32_e32 v67, v40, v18
	v_fmac_f32_e32 v68, v47, v15
	ds_bpermute_b32 v5, v222, v5
	v_cndmask_b32_e64 v6, v236, v135, s[6:7]
	s_waitcnt lgkmcnt(5)
	v_add_f32_e32 v0, v20, v0
	v_cndmask_b32_e64 v20, v125, v212, s[6:7]
	v_fmac_f32_e32 v176, v167, v96
	v_fmac_f32_e32 v177, v166, v101
	v_fmac_f32_e32 v178, v165, v70
	v_fmac_f32_e32 v131, v8, v123
	v_fmac_f32_e32 v130, v9, v70
	v_fmac_f32_e32 v129, v10, v101
	v_fmac_f32_e32 v128, v11, v96
	v_fmac_f32_e32 v63, v43, v28
	v_fmac_f32_e32 v66, v42, v25
	v_fmac_f32_e32 v67, v41, v22
	v_fmac_f32_e32 v68, v40, v19
	ds_bpermute_b32 v6, v222, v6
	v_cndmask_b32_e64 v7, v188, v164, s[6:7]
	s_waitcnt lgkmcnt(5)
	v_add_f32_e32 v1, v20, v1
	v_cndmask_b32_e64 v20, v126, v213, s[6:7]
	v_fmac_f32_e32 v177, v167, v97
	v_fmac_f32_e32 v178, v166, v102
	v_fmac_f32_e32 v179, v165, v71
	v_fmac_f32_e32 v131, v9, v71
	v_fmac_f32_e32 v130, v10, v102
	v_fmac_f32_e32 v129, v11, v97
	v_fmac_f32_e32 v63, v8, v32
	v_fmac_f32_e32 v66, v43, v29
	v_fmac_f32_e32 v67, v42, v26
	v_fmac_f32_e32 v68, v41, v23
	ds_bpermute_b32 v7, v222, v7
	v_cndmask_b32_e64 v12, v176, v128, s[6:7]
	s_waitcnt lgkmcnt(5)
	v_add_f32_e32 v2, v20, v2
	v_cndmask_b32_e64 v20, v127, v233, s[6:7]
	v_fmac_f32_e32 v178, v167, v98
	v_fmac_f32_e32 v179, v166, v103
	v_fmac_f32_e32 v180, v165, v36
	v_fmac_f32_e32 v131, v10, v103
	v_fmac_f32_e32 v130, v11, v98
	v_fmac_f32_e32 v63, v9, v36
	v_fmac_f32_e32 v66, v8, v33
	v_fmac_f32_e32 v67, v43, v30
	v_fmac_f32_e32 v68, v42, v27
	ds_bpermute_b32 v12, v222, v12
	v_cndmask_b32_e64 v13, v177, v129, s[6:7]
	s_waitcnt lgkmcnt(5)
	v_add_f32_e32 v3, v20, v3
	v_cndmask_b32_e64 v20, v133, v234, s[6:7]
	v_fmac_f32_e32 v179, v167, v99
	v_fmac_f32_e32 v180, v166, v52
	v_fmac_f32_e32 v181, v165, v37
	v_fmac_f32_e32 v131, v11, v99
	v_fmac_f32_e32 v63, v10, v52
	v_fmac_f32_e32 v66, v9, v37
	v_fmac_f32_e32 v67, v8, v34
	v_fmac_f32_e32 v68, v43, v31
	ds_bpermute_b32 v13, v222, v13
	v_cndmask_b32_e64 v14, v178, v130, s[6:7]
	s_waitcnt lgkmcnt(5)
	v_add_f32_e32 v4, v20, v4
	v_cndmask_b32_e64 v20, v134, v235, s[6:7]
	v_fmac_f32_e32 v180, v167, v56
	v_fmac_f32_e32 v181, v166, v53
	v_fmac_f32_e32 v182, v165, v38
	v_fmac_f32_e32 v63, v11, v56
	v_fmac_f32_e32 v66, v10, v53
	v_fmac_f32_e32 v67, v9, v38
	v_fmac_f32_e32 v68, v8, v35
	ds_bpermute_b32 v14, v222, v14
	v_cndmask_b32_e64 v15, v179, v131, s[6:7]
	s_waitcnt lgkmcnt(5)
	v_add_f32_e32 v5, v20, v5
	v_cndmask_b32_e64 v20, v135, v236, s[6:7]
	v_fmac_f32_e32 v181, v167, v57
	v_fmac_f32_e32 v182, v166, v54
	v_fmac_f32_e32 v132, v165, v39
	v_fmac_f32_e32 v66, v11, v57
	v_fmac_f32_e32 v67, v10, v54
	v_fmac_f32_e32 v68, v9, v39
	ds_bpermute_b32 v15, v222, v15
	v_cndmask_b32_e64 v16, v180, v63, s[6:7]
	s_waitcnt lgkmcnt(5)
	v_add_f32_e32 v6, v20, v6
	v_cndmask_b32_e64 v20, v164, v188, s[6:7]
	v_fmac_f32_e32 v182, v167, v58
	v_fmac_f32_e32 v132, v166, v55
	v_fmac_f32_e32 v67, v11, v58
	v_fmac_f32_e32 v68, v10, v55
	ds_bpermute_b32 v16, v222, v16
	v_cndmask_b32_e64 v17, v181, v66, s[6:7]
	s_waitcnt lgkmcnt(5)
	v_add_f32_e32 v7, v20, v7
	v_cndmask_b32_e64 v20, v128, v176, s[6:7]
	v_fmac_f32_e32 v132, v167, v59
	v_fmac_f32_e32 v68, v11, v59
	ds_bpermute_b32 v17, v222, v17
	v_cndmask_b32_e64 v18, v182, v67, s[6:7]
	s_waitcnt lgkmcnt(5)
	v_add_f32_e32 v12, v20, v12
	v_cndmask_b32_e64 v20, v129, v177, s[6:7]
	ds_bpermute_b32 v18, v222, v18
	v_cndmask_b32_e64 v19, v132, v68, s[6:7]
	s_waitcnt lgkmcnt(5)
	v_add_f32_e32 v13, v20, v13
	v_cndmask_b32_e64 v20, v130, v178, s[6:7]
	ds_bpermute_b32 v19, v222, v19
	s_waitcnt lgkmcnt(5)
	v_add_f32_e32 v14, v20, v14
	v_cndmask_b32_e64 v20, v131, v179, s[6:7]
	s_waitcnt lgkmcnt(4)
	v_add_f32_e32 v15, v20, v15
	v_cndmask_b32_e64 v20, v63, v180, s[6:7]
	s_waitcnt lgkmcnt(3)
	v_add_f32_e32 v16, v20, v16
	v_cndmask_b32_e64 v20, v66, v181, s[6:7]
	s_waitcnt lgkmcnt(2)
	v_add_f32_e32 v17, v20, v17
	v_cndmask_b32_e64 v20, v67, v182, s[6:7]
	s_waitcnt lgkmcnt(1)
	v_add_f32_e32 v18, v20, v18
	v_cndmask_b32_e64 v20, v68, v132, s[6:7]
	s_waitcnt lgkmcnt(0)
	v_add_f32_e32 v19, v20, v19
	v_cndmask_b32_e64 v20, v0, v12, s[8:9]
	v_cndmask_b32_e64 v24, v4, v16, s[8:9]
	ds_bpermute_b32 v20, v221, v20
	v_cndmask_b32_e64 v21, v1, v13, s[8:9]
	ds_bpermute_b32 v24, v221, v24
	v_cndmask_b32_e64 v25, v5, v17, s[8:9]
	ds_bpermute_b32 v21, v221, v21
	v_cndmask_b32_e64 v22, v2, v14, s[8:9]
	ds_bpermute_b32 v25, v221, v25
	v_cndmask_b32_e64 v26, v6, v18, s[8:9]
	ds_bpermute_b32 v22, v221, v22
	v_cndmask_b32_e64 v23, v3, v15, s[8:9]
	ds_bpermute_b32 v26, v221, v26
	v_cndmask_b32_e64 v27, v7, v19, s[8:9]
	ds_bpermute_b32 v23, v221, v23
	ds_bpermute_b32 v27, v221, v27
	v_cndmask_b32_e64 v0, v12, v0, s[8:9]
	v_cndmask_b32_e64 v4, v16, v4, s[8:9]
	s_waitcnt lgkmcnt(7)
	v_add_f32_e32 v0, v0, v20
	v_cndmask_b32_e64 v1, v13, v1, s[8:9]
	s_waitcnt lgkmcnt(6)
	v_add_f32_e32 v4, v4, v24
	v_cndmask_b32_e64 v5, v17, v5, s[8:9]
	s_waitcnt lgkmcnt(5)
	v_add_f32_e32 v1, v1, v21
	v_cndmask_b32_e64 v2, v14, v2, s[8:9]
	s_waitcnt lgkmcnt(4)
	v_add_f32_e32 v5, v5, v25
	v_cndmask_b32_e64 v6, v18, v6, s[8:9]
	v_cndmask_b32_e64 v12, v0, v4, s[10:11]
	s_waitcnt lgkmcnt(3)
	v_add_f32_e32 v2, v2, v22
	v_cndmask_b32_e64 v3, v15, v3, s[8:9]
	s_waitcnt lgkmcnt(2)
	v_add_f32_e32 v6, v6, v26
	v_cndmask_b32_e64 v7, v19, v7, s[8:9]
	ds_bpermute_b32 v12, v220, v12
	v_cndmask_b32_e64 v13, v1, v5, s[10:11]
	s_waitcnt lgkmcnt(2)
	v_add_f32_e32 v3, v3, v23
	s_waitcnt lgkmcnt(1)
	v_add_f32_e32 v7, v7, v27
	ds_bpermute_b32 v13, v220, v13
	v_cndmask_b32_e64 v14, v2, v6, s[10:11]
	ds_bpermute_b32 v14, v220, v14
	v_cndmask_b32_e64 v15, v3, v7, s[10:11]
	ds_bpermute_b32 v15, v220, v15
	v_cndmask_b32_e64 v0, v4, v0, s[10:11]
	s_waitcnt lgkmcnt(3)
	v_add_f32_e32 v4, v0, v12
	v_cndmask_b32_e64 v0, v5, v1, s[10:11]
	s_waitcnt lgkmcnt(2)
	v_add_f32_e32 v1, v0, v13
	v_cndmask_b32_e64 v0, v6, v2, s[10:11]
	s_waitcnt lgkmcnt(1)
	v_add_f32_e32 v2, v0, v14
	v_cndmask_b32_e64 v0, v7, v3, s[10:11]
	s_waitcnt lgkmcnt(0)
	v_add_f32_e32 v3, v0, v15
	v_cndmask_b32_e64 v0, v4, v2, s[12:13]
	ds_bpermute_b32 v5, v219, v0
	v_cndmask_b32_e64 v0, v1, v3, s[12:13]
	ds_bpermute_b32 v6, v219, v0
	v_cndmask_b32_e64 v2, v2, v4, s[12:13]
	v_cndmask_b32_e64 v1, v3, v1, s[12:13]
	s_waitcnt lgkmcnt(1)
	v_add_f32_e32 v4, v2, v5
	v_cvt_pk_bf16_f32 v0, v64, v65
	s_waitcnt lgkmcnt(0)
	v_add_f32_e32 v5, v1, v6
	v_cndmask_b32_e64 v1, v4, v5, s[14:15]
	ds_bpermute_b32 v6, v218, v1
	v_cvt_pk_bf16_f32 v1, v48, v49
	global_store_dwordx2 v[50:51], v[0:1], off offset:1024
	v_cndmask_b32_e64 v0, v5, v4, s[14:15]
	v_pk_mul_f32 v[4:5], v[8:9], v[62:63] op_sel_hi:[1,0]
	s_waitcnt lgkmcnt(0)
	v_add_f32_e32 v0, v0, v6
	ds_bpermute_b32 v1, v217, v0
	v_cmp_lt_i32_e64 s[0:1], 0, v223
	v_pk_mul_f32 v[2:3], v[10:11], v[62:63] op_sel_hi:[1,0]
	v_cvt_pk_bf16_f32 v4, v4, v5
	s_nop 0
	v_cvt_pk_bf16_f32 v5, v2, v3
	global_store_dwordx2 v[50:51], v[4:5], off offset:1536
	s_and_saveexec_b64 s[2:3], s[0:1]
	s_cbranch_execz .LBB0_150
	v_cmp_ne_u32_e64 s[0:1], 1, v223
	s_and_saveexec_b64 s[36:37], s[0:1]
	s_xor_b64 s[0:1], exec, s[36:37]
	v_cndmask_b32_e32 v231, v60, v210, vcc
	s_andn2_saveexec_b64 s[0:1], s[0:1]
	v_mov_b32_e32 v231, v232
	s_or_b64 exec, exec, s[0:1]
